# adds: merge epilogue b_merge loads issued together; head-norm gain loads of the chunk-output epilogues hoisted with counted waits
# speedup vs baseline: 1.0126x; 1.0126x over previous
;   __device__ __forceinline__ bf16* h() const { unsigned o_ = (unsigned)(OFF_h); asm volatile("" : "+s"(o_)); return (bf16*)(ws + o_); }
;   __device__ __forceinline__ bf16* y() const { unsigned o_ = (unsigned)(OFF_y); asm volatile("" : "+s"(o_)); return (bf16*)(ws + o_); }
; template <int MX>
; __device__ void out_unit(const P& p, int layer, int unit, char* smem) {
;     ...
; #pragma unroll
;   for (int kb = 0; kb < DK / 32; ++kb) {
;     const bf16x8 a = *(const bf16x8*)(Qs + (16 * w + r) * 72 + kb * 32 + q4 * 8);
; #pragma unroll
;     for (int et = 0; et < NE; ++et) {
;       const bf16x8 bs = *(const bf16x8*)(St + (16 * et + r) * 72 + kb * 32 + q4 * 8);
;       o2[et] = MFMA(bs, a, o2[et]);
;     }
;   }
;   const float* ng = ((MX == 0) ? p.gla_norm : (MX == 1 ? p.ml_norm : p.ret_norm)) + layer * 256 + h * 64 + 4 * q4;
;   {
;     const int qq = 16 * w + r;
;     float rsc = 1.f;
;     if (MX == 1) rsc = __expf(mprev - va[qq]);
;     if (MX == 2) rsc = exp2f((float)(qq + 1) * l2g);
;     f32x4 ov[4];
; #pragma unroll
;     for (int et = 0; et < 4; ++et) ov[et] = o[et] + o2[et] * rsc;
;     if (MX == 1) {
;       float den = o[NE - 1][0] + rsc * o2[NE - 1][0];
;       den = __shfl(den, r);
;       const float fl = __expf(-(vc[qq] + va[qq]));
;       const float inv = 1.f / fmaxf(fabsf(den), fl);
; #pragma unroll
;       for (int et = 0; et < 4; ++et) ov[et] = ov[et] * inv;
;     }
;     float ss = 0.f;
; #pragma unroll
;     for (int et = 0; et < 4; ++et) ss += ov[et][0] * ov[et][0] + ov[et][1] * ov[et][1] + ov[et][2] * ov[et][2] + ov[et][3] * ov[et][3];
;     ss += __shfl_xor(ss, 16); ss += __shfl_xor(ss, 32);
;     const float rms = rsqrtf(ss * (1.f / 64.f) + EPS);
;     bf16* yp = p.y() + TROW(qq) * D + (MX + 1) * 256 + h * 64 + 4 * q4;
; #pragma unroll
;     for (int et = 0; et < 4; ++et) {
;       const float4 g4 = *(const float4*)(ng + 16 * et);
;       const float t0 = lo16(gpre[et].x), t1 = hi16(gpre[et].x), t2 = lo16(gpre[et].y), t3 = hi16(gpre[et].y);
;       const float a0 = (MX == 1) ? sigm(t0) : silu(t0), a1 = (MX == 1) ? sigm(t1) : silu(t1), a2 = (MX == 1) ? sigm(t2) : silu(t2), a3 = (MX == 1) ? sigm(t3) : silu(t3);
;       uint2 ov2;
;       ov2.x = pk2(ov[et][0] * rms * g4.x * a0, ov[et][1] * rms * g4.y * a1);
;       ov2.y = pk2(ov[et][2] * rms * g4.z * a2, ov[et][3] * rms * g4.w * a3);
;       *(uint2*)(yp + 16 * et) = ov2;
;     }
.LBB0_503:
	s_or_b64 exec, exec, s[0:1]
	v_readlane_b32 s0, v254, 57
	ds_read_b128 v[32:35], v28
	s_nop 0
	v_lshl_add_u32 v48, v138, 1, s0
	v_mad_u32_u24 v25, v25, s50, v48
	v_mad_i32_i24 v56, v31, s50, v48
	v_mad_i32_i24 v57, v30, s50, v48
	v_mad_i32_i24 v29, v29, s50, v48
	ds_read_b128 v[36:39], v25
	ds_read_b128 v[40:43], v56
	ds_read_b128 v[48:51], v29
	ds_read_b128 v[44:47], v57
	s_waitcnt lgkmcnt(3)
	v_mfma_f32_16x16x32_bf16 v[36:39], v[36:39], v[32:35], 0
	s_lshl_b32 s0, s4, 2
	s_add_u32 s2, s60, s0
	s_mov_b32 s0, 0xc2fc0000
	s_waitcnt lgkmcnt(2)
	v_mfma_f32_16x16x32_bf16 v[40:43], v[40:43], v[32:35], 0
	s_addc_u32 s3, s62, 0
	v_lshlrev_b32_e32 v138, 1, v27
	s_waitcnt lgkmcnt(0)
	v_mfma_f32_16x16x32_bf16 v[44:47], v[44:47], v[32:35], 0
	v_mfma_f32_16x16x32_bf16 v[30:33], v[48:51], v[32:35], 0
	ds_read_b128 v[48:51], v28 offset:64
	ds_read_b128 v[52:55], v25 offset:64
	v_add_u32_e32 v25, 1, v26
	v_cvt_f32_i32_e32 v25, v25
	s_waitcnt lgkmcnt(0)
	v_mfma_f32_16x16x32_bf16 v[34:37], v[52:55], v[48:51], v[36:39]
	ds_read_b128 v[52:55], v56 offset:64
	v_mul_f32_e32 v28, v24, v25
	v_cmp_gt_f32_e64 s[0:1], s0, v28
	s_waitcnt lgkmcnt(0)
	v_mfma_f32_16x16x32_bf16 v[38:41], v[52:55], v[48:51], v[40:43]
	ds_read_b128 v[52:55], v57 offset:64
	v_cndmask_b32_e64 v28, 0, v194, s[0:1]
	v_fmac_f32_e32 v28, v24, v25
	s_waitcnt lgkmcnt(0)
	v_mfma_f32_16x16x32_bf16 v[42:45], v[52:55], v[48:51], v[44:47]
	ds_read_b128 v[52:55], v29 offset:64
	v_exp_f32_e32 v24, v28
	v_cndmask_b32_e64 v25, 0, v195, s[0:1]
	s_waitcnt lgkmcnt(0)
	v_mfma_f32_16x16x32_bf16 v[46:49], v[52:55], v[48:51], v[30:33]
	s_nop 2
	v_ldexp_f32 v32, v24, v25
	v_pk_fma_f32 v[30:31], v[32:33], v[34:35], v[4:5] op_sel_hi:[0,1,1]
	v_pk_fma_f32 v[24:25], v[32:33], v[38:39], v[12:13] op_sel_hi:[0,1,1]
	v_pk_fma_f32 v[28:29], v[32:33], v[36:37], v[6:7] op_sel_hi:[0,1,1]
	s_nop 0
	v_pk_fma_f32 v[6:7], v[32:33], v[48:49], v[2:3] op_sel_hi:[0,1,1]
	v_mov_b32_e32 v2, v31
	v_mov_b32_e32 v3, v25
	v_pk_fma_f32 v[14:15], v[32:33], v[40:41], v[14:15] op_sel_hi:[0,1,1]
	v_pk_fma_f32 v[12:13], v[32:33], v[42:43], v[8:9] op_sel_hi:[0,1,1]
	v_pk_fma_f32 v[8:9], v[32:33], v[46:47], v[0:1] op_sel_hi:[0,1,1]
	v_mov_b32_e32 v0, v30
	v_mov_b32_e32 v1, v24
	v_pk_mul_f32 v[2:3], v[2:3], v[2:3]
	v_mov_b32_e32 v4, v13
	v_pk_fma_f32 v[0:1], v[0:1], v[0:1], v[2:3]
	v_mov_b32_e32 v2, v28
	v_mov_b32_e32 v3, v14
	v_pk_fma_f32 v[0:1], v[2:3], v[2:3], v[0:1]
	v_mov_b32_e32 v2, v29
	v_mov_b32_e32 v3, v15
	v_mov_b32_e32 v5, v9
	v_pk_fma_f32 v[10:11], v[32:33], v[44:45], v[10:11] op_sel_hi:[0,1,1]
	v_pk_fma_f32 v[0:1], v[2:3], v[2:3], v[0:1]
	v_mov_b32_e32 v2, v12
	v_mov_b32_e32 v3, v8
	v_pk_mul_f32 v[4:5], v[4:5], v[4:5]
	v_add_f32_e32 v0, v0, v1
	v_pk_fma_f32 v[2:3], v[2:3], v[2:3], v[4:5]
	v_mov_b32_e32 v4, v10
	v_mov_b32_e32 v5, v6
	v_pk_fma_f32 v[2:3], v[4:5], v[4:5], v[2:3]
	v_mov_b32_e32 v4, v11
	v_mov_b32_e32 v5, v7
	v_pk_fma_f32 v[2:3], v[4:5], v[4:5], v[2:3]
	v_xor_b32_e32 v1, 16, v198
	v_add_f32_e32 v0, v0, v2
	v_and_b32_e32 v2, 64, v198
	v_add_u32_e32 v2, 64, v2
	v_cmp_lt_i32_e64 s[0:1], v1, v2
	v_add_f32_e32 v0, v0, v3
	v_lshlrev_b32_e32 v33, 2, v27
	v_cndmask_b32_e64 v1, v198, v1, s[0:1]
	v_lshlrev_b32_e32 v1, 2, v1
	ds_bpermute_b32 v1, v1, v0
	v_lshlrev_b32_e32 v34, 16, v22
	v_mul_f32_e32 v36, 0xbfb8aa3b, v34
	v_exp_f32_e32 v36, v36
	v_and_b32_e32 v22, 0xffff0000, v22
	s_waitcnt lgkmcnt(0)
	v_add_f32_e32 v0, v0, v1
	v_xor_b32_e32 v1, 32, v198
	v_cmp_lt_i32_e64 s[0:1], v1, v2
	v_add_f32_e32 v36, 1.0, v36
	v_rcp_f32_e32 v36, v36
	v_cndmask_b32_e64 v1, v198, v1, s[0:1]
	v_lshlrev_b32_e32 v1, 2, v1
	ds_bpermute_b32 v1, v1, v0
	v_mul_f32_e32 v34, v36, v34
	v_mul_f32_e32 v36, 0xbfb8aa3b, v22
	v_exp_f32_e32 v36, v36
	v_lshlrev_b32_e32 v35, 16, v23
	s_waitcnt lgkmcnt(0)
	v_add_f32_e32 v0, v0, v1
	v_fmamk_f32 v0, v0, 0x3c800000, v193
	v_cmp_gt_f32_e64 s[0:1], s92, v0
	v_mul_f32_e32 v1, 0x4b800000, v0
	v_add_f32_e32 v36, 1.0, v36
	v_cndmask_b32_e64 v0, v0, v1, s[0:1]
	v_rsq_f32_e32 v0, v0
	v_rcp_f32_e32 v36, v36
	v_and_b32_e32 v23, 0xffff0000, v23
	v_mul_f32_e32 v1, 0x45800000, v0
	v_cndmask_b32_e64 v32, v0, v1, s[0:1]
	v_mov_b32_e32 v0, s12
	v_mov_b32_e32 v1, s13
	s_mov_b32 s0, 0x15603000
	v_cndmask_b32_e32 v0, v0, v1, vcc
	v_add_u32_e32 v0, v0, v26
	s_add_u32 s0, s76, s0
	v_ashrrev_i32_e32 v1, 31, v0
	s_addc_u32 s1, s77, 0
	v_lshlrev_b64 v[0:1], 11, v[0:1]
	v_lshl_add_u64 v[0:1], s[0:1], 0, v[0:1]
	s_lshl_b32 s96, s4, 1
	v_lshl_add_u64 v[0:1], v[0:1], 0, s[96:97]
	v_lshl_add_u64 v[26:27], v[0:1], 0, v[138:139]
	global_load_dwordx4 v[0:3], v33, s[2:3]
	global_load_dwordx4 v[210:213], v33, s[2:3] offset:64
	global_load_dwordx4 v[214:217], v33, s[2:3] offset:128
	global_load_dwordx4 v[218:221], v33, s[2:3] offset:192
	v_mul_f32_e32 v22, v36, v22
	v_mul_f32_e32 v36, 0xbfb8aa3b, v35
	v_exp_f32_e32 v36, v36
	v_mul_f32_e32 v30, v30, v32
	v_mul_f32_e32 v24, v24, v32
	v_mul_f32_e32 v12, v12, v32
	v_add_f32_e32 v36, 1.0, v36
	v_rcp_f32_e32 v36, v36
	s_mov_b64 s[0:1], 0x600
	v_lshl_add_u64 v[4:5], v[26:27], 0, s[0:1]
	s_mov_b64 s[0:1], 0
	v_mul_f32_e32 v35, v36, v35
	v_mul_f32_e32 v36, 0xbfb8aa3b, v23
	v_exp_f32_e32 v36, v36
	s_waitcnt vmcnt(3)
;   __device__ __forceinline__ bf16* y() const { unsigned o_ = (unsigned)(OFF_y); asm volatile("" : "+s"(o_)); return (bf16*)(ws + o_); }
; __device__ __forceinline__ unsigned pk2(float a, float b) { unsigned r; asm("v_cvt_pk_bf16_f32 %0, %1, %2" : "=v"(r) : "v"(a), "v"(b)); return r; }
; __device__ __forceinline__ float lo16(unsigned v) { return __uint_as_float(v << 16); }
; __device__ __forceinline__ float hi16(unsigned v) { return __uint_as_float(v & 0xffff0000u); }
; __device__ __forceinline__ float sigm(float x) { return __builtin_amdgcn_rcpf(1.f + __expf(-x)); }
; __device__ __forceinline__ float silu(float x) { return x * sigm(x); }
; template <int MX>
; __device__ void out_unit(const P& p, int layer, int unit, char* smem) {
;     ...
; #pragma unroll
;     for (int et = 0; et < 4; ++et) {
;       const float4 g4 = *(const float4*)(ng + 16 * et);
;       const float t0 = lo16(gpre[et].x), t1 = hi16(gpre[et].x), t2 = lo16(gpre[et].y), t3 = hi16(gpre[et].y);
;       const float a0 = (MX == 1) ? sigm(t0) : silu(t0), a1 = (MX == 1) ? sigm(t1) : silu(t1), a2 = (MX == 1) ? sigm(t2) : silu(t2), a3 = (MX == 1) ? sigm(t3) : silu(t3);
;       uint2 ov2;
;       ov2.x = pk2(ov[et][0] * rms * g4.x * a0, ov[et][1] * rms * g4.y * a1);
;       ov2.y = pk2(ov[et][2] * rms * g4.z * a2, ov[et][3] * rms * g4.w * a3);
;       *(uint2*)(yp + 16 * et) = ov2;
;     }
	v_mul_f32_e32 v0, v0, v30
	v_add_f32_e32 v36, 1.0, v36
	v_mul_f32_e32 v30, v31, v32
	v_rcp_f32_e32 v36, v36
	v_mul_f32_e32 v1, v1, v30
	v_mul_f32_e32 v0, v34, v0
	v_mul_f32_e32 v1, v22, v1
	v_cvt_pk_bf16_f32 v0, v0, v1
	v_mul_f32_e32 v1, v28, v32
	v_mul_f32_e32 v1, v2, v1
	v_mul_f32_e32 v2, v29, v32
	v_mul_f32_e32 v23, v36, v23
	v_mul_f32_e32 v1, v35, v1
	v_mul_f32_e32 v2, v3, v2
	v_mul_f32_e32 v2, v23, v2
	v_cvt_pk_bf16_f32 v1, v1, v2
	global_store_dwordx2 v[26:27], v[0:1], off offset:1536
	s_waitcnt vmcnt(3)
	s_nop 0
	v_mov_b32_e32 v0, v210
	v_mov_b32_e32 v1, v211
	v_mov_b32_e32 v2, v212
	v_mov_b32_e32 v3, v213
	v_lshlrev_b32_e32 v22, 16, v20
	v_mul_f32_e32 v28, 0xbfb8aa3b, v22
	v_exp_f32_e32 v28, v28
	v_and_b32_e32 v20, 0xffff0000, v20
	v_lshlrev_b32_e32 v23, 16, v21
	v_and_b32_e32 v21, 0xffff0000, v21
	v_add_f32_e32 v28, 1.0, v28
	v_rcp_f32_e32 v28, v28
	s_nop 0
	v_mul_f32_e32 v0, v0, v24
	v_mul_f32_e32 v22, v28, v22
	v_mul_f32_e32 v28, 0xbfb8aa3b, v20
	v_exp_f32_e32 v28, v28
	v_mul_f32_e32 v0, v22, v0
	v_mul_f32_e32 v22, v25, v32
	v_mul_f32_e32 v1, v1, v22
	v_add_f32_e32 v28, 1.0, v28
	v_rcp_f32_e32 v28, v28
	v_mul_f32_e32 v25, v7, v32
	v_mul_f32_e32 v20, v28, v20
	v_mul_f32_e32 v28, 0xbfb8aa3b, v23
	v_exp_f32_e32 v28, v28
	v_mul_f32_e32 v1, v20, v1
	v_cvt_pk_bf16_f32 v0, v0, v1
	v_mul_f32_e32 v1, v14, v32
	v_add_f32_e32 v28, 1.0, v28
	v_rcp_f32_e32 v28, v28
	v_mul_f32_e32 v1, v2, v1
	v_mul_f32_e32 v2, v15, v32
	v_mul_f32_e32 v2, v3, v2
	v_mul_f32_e32 v23, v28, v23
	v_mul_f32_e32 v28, 0xbfb8aa3b, v21
	v_exp_f32_e32 v28, v28
	v_mul_f32_e32 v1, v23, v1
	v_lshlrev_b32_e32 v14, 16, v18
	v_mul_f32_e32 v20, 0xbfb8aa3b, v14
	v_add_f32_e32 v28, 1.0, v28
	v_rcp_f32_e32 v28, v28
	v_exp_f32_e32 v20, v20
	v_and_b32_e32 v15, 0xffff0000, v18
	v_lshlrev_b32_e32 v18, 16, v19
	v_mul_f32_e32 v21, v28, v21
	v_mul_f32_e32 v2, v21, v2
	v_cvt_pk_bf16_f32 v1, v1, v2
	global_store_dwordx2 v[26:27], v[0:1], off offset:1568
	s_waitcnt vmcnt(3)
	s_nop 0
	v_mov_b32_e32 v0, v214
	v_mov_b32_e32 v1, v215
	v_mov_b32_e32 v2, v216
	v_mov_b32_e32 v3, v217
	v_add_f32_e32 v20, 1.0, v20
	v_rcp_f32_e32 v20, v20
	v_and_b32_e32 v19, 0xffff0000, v19
	v_mul_f32_e32 v21, v9, v32
	v_mul_f32_e32 v23, v6, v32
	v_mul_f32_e32 v14, v20, v14
	v_mul_f32_e32 v20, 0xbfb8aa3b, v15
	v_exp_f32_e32 v20, v20
	s_nop 0
	v_mul_f32_e32 v0, v12, v0
	v_add_f32_e32 v20, 1.0, v20
	v_rcp_f32_e32 v20, v20
	v_mul_f32_e32 v12, v13, v32
	v_mul_f32_e32 v1, v12, v1
	v_mul_f32_e32 v0, v14, v0
	v_mul_f32_e32 v15, v20, v15
	v_mul_f32_e32 v20, 0xbfb8aa3b, v18
	v_exp_f32_e32 v20, v20
	v_mul_f32_e32 v1, v15, v1
	v_cvt_pk_bf16_f32 v0, v0, v1
	v_mul_f32_e32 v1, v10, v32
	v_add_f32_e32 v20, 1.0, v20
	v_rcp_f32_e32 v20, v20
	v_mul_f32_e32 v1, v1, v2
	v_mul_f32_e32 v2, v11, v32
	v_mul_f32_e32 v2, v2, v3
	v_mul_f32_e32 v18, v20, v18
	v_mul_f32_e32 v20, 0xbfb8aa3b, v19
	v_exp_f32_e32 v20, v20
	v_mul_f32_e32 v1, v18, v1
	v_lshlrev_b32_e32 v10, 16, v16
	v_mul_f32_e32 v11, 0xbfb8aa3b, v10
	v_add_f32_e32 v20, 1.0, v20
	v_rcp_f32_e32 v20, v20
	v_exp_f32_e32 v11, v11
	v_and_b32_e32 v12, 0xffff0000, v16
	v_lshlrev_b32_e32 v14, 16, v17
	v_mul_f32_e32 v19, v20, v19
	v_mul_f32_e32 v2, v19, v2
	v_cvt_pk_bf16_f32 v1, v1, v2
	global_store_dwordx2 v[26:27], v[0:1], off offset:1600
	s_waitcnt vmcnt(3)
	s_nop 0
	v_mov_b32_e32 v0, v218
	v_mov_b32_e32 v1, v219
	v_mov_b32_e32 v2, v220
	v_mov_b32_e32 v3, v221
	v_add_f32_e32 v11, 1.0, v11
	v_rcp_f32_e32 v18, v11
	v_mul_f32_e32 v11, 0xbfb8aa3b, v12
	v_exp_f32_e32 v11, v11
	v_and_b32_e32 v16, 0xffff0000, v17
	v_mul_f32_e32 v19, v8, v32
	v_add_f32_e32 v11, 1.0, v11
	v_rcp_f32_e32 v20, v11
	v_mul_f32_e32 v11, 0xbfb8aa3b, v14
	v_exp_f32_e32 v11, v11
	s_nop 0
	v_mov_b32_e32 v13, v1
	v_add_f32_e32 v11, 1.0, v11
	v_rcp_f32_e32 v22, v11
	v_mul_f32_e32 v11, 0xbfb8aa3b, v16
	v_exp_f32_e32 v11, v11
	v_mov_b32_e32 v15, v2
	v_mov_b32_e32 v17, v3
	v_add_f32_e32 v11, 1.0, v11
	v_rcp_f32_e32 v24, v11
	v_mov_b32_e32 v11, v0
	v_pk_mul_f32 v[10:11], v[18:19], v[10:11]
	v_pk_mul_f32 v[0:1], v[20:21], v[12:13]
	v_mul_f32_e32 v8, v10, v11
	v_mul_f32_e32 v0, v0, v1
	v_cvt_pk_bf16_f32 v0, v8, v0
	v_pk_mul_f32 v[8:9], v[22:23], v[14:15]
	v_pk_mul_f32 v[2:3], v[24:25], v[16:17]
	v_mul_f32_e32 v1, v8, v9
	v_mul_f32_e32 v2, v2, v3
	v_cvt_pk_bf16_f32 v1, v1, v2

;   __device__ __forceinline__ bf16* h() const { unsigned o_ = (unsigned)(OFF_h); asm volatile("" : "+s"(o_)); return (bf16*)(ws + o_); }
;   __device__ __forceinline__ bf16* y() const { unsigned o_ = (unsigned)(OFF_y); asm volatile("" : "+s"(o_)); return (bf16*)(ws + o_); }
; template <int MX>
; __device__ void out_unit(const P& p, int layer, int unit, char* smem) {
;     ...
; #pragma unroll
;   for (int kb = 0; kb < DK / 32; ++kb) {
;     const bf16x8 a = *(const bf16x8*)(Qs + (16 * w + r) * 72 + kb * 32 + q4 * 8);
; #pragma unroll
;     for (int et = 0; et < NE; ++et) {
;       const bf16x8 bs = *(const bf16x8*)(St + (16 * et + r) * 72 + kb * 32 + q4 * 8);
;       o2[et] = MFMA(bs, a, o2[et]);
;     }
;   }
;   const float* ng = ((MX == 0) ? p.gla_norm : (MX == 1 ? p.ml_norm : p.ret_norm)) + layer * 256 + h * 64 + 4 * q4;
;   {
;     const int qq = 16 * w + r;
;     float rsc = 1.f;
;     if (MX == 1) rsc = __expf(mprev - va[qq]);
;     if (MX == 2) rsc = exp2f((float)(qq + 1) * l2g);
;     f32x4 ov[4];
; #pragma unroll
;     for (int et = 0; et < 4; ++et) ov[et] = o[et] + o2[et] * rsc;
;     if (MX == 1) {
;       float den = o[NE - 1][0] + rsc * o2[NE - 1][0];
;       den = __shfl(den, r);
;       const float fl = __expf(-(vc[qq] + va[qq]));
;       const float inv = 1.f / fmaxf(fabsf(den), fl);
; #pragma unroll
;       for (int et = 0; et < 4; ++et) ov[et] = ov[et] * inv;
;     }
;     float ss = 0.f;
; #pragma unroll
;     for (int et = 0; et < 4; ++et) ss += ov[et][0] * ov[et][0] + ov[et][1] * ov[et][1] + ov[et][2] * ov[et][2] + ov[et][3] * ov[et][3];
;     ss += __shfl_xor(ss, 16); ss += __shfl_xor(ss, 32);
;     const float rms = rsqrtf(ss * (1.f / 64.f) + EPS);
;     bf16* yp = p.y() + TROW(qq) * D + (MX + 1) * 256 + h * 64 + 4 * q4;
; #pragma unroll
;     for (int et = 0; et < 4; ++et) {
;       const float4 g4 = *(const float4*)(ng + 16 * et);
;       const float t0 = lo16(gpre[et].x), t1 = hi16(gpre[et].x), t2 = lo16(gpre[et].y), t3 = hi16(gpre[et].y);
;       const float a0 = (MX == 1) ? sigm(t0) : silu(t0), a1 = (MX == 1) ? sigm(t1) : silu(t1), a2 = (MX == 1) ? sigm(t2) : silu(t2), a3 = (MX == 1) ? sigm(t3) : silu(t3);
;       uint2 ov2;
;       ov2.x = pk2(ov[et][0] * rms * g4.x * a0, ov[et][1] * rms * g4.y * a1);
;       ov2.y = pk2(ov[et][2] * rms * g4.z * a2, ov[et][3] * rms * g4.w * a3);
;       *(uint2*)(yp + 16 * et) = ov2;
;     }
.LBB0_524:
	s_or_b64 exec, exec, s[0:1]
	v_readlane_b32 s0, v254, 57
	ds_read_b128 v[34:37], v25
	s_nop 0
	v_lshl_add_u32 v25, v138, 1, s0
	v_mad_u32_u24 v24, v24, s50, v25
	ds_read_b128 v[38:41], v24
	v_mad_i32_i24 v24, v28, s50, v25
	ds_read_b128 v[28:31], v24
	v_mad_i32_i24 v24, v27, s50, v25
	s_lshl_b32 s0, s96, 2
	s_add_u32 s2, s65, s0
	s_addc_u32 s3, s66, 0
	s_waitcnt lgkmcnt(1)
	v_mfma_f32_16x16x32_bf16 v[38:41], v[38:41], v[34:37], 0
	v_lshlrev_b32_e32 v138, 1, v33
	s_waitcnt lgkmcnt(0)
	v_mfma_f32_16x16x32_bf16 v[42:45], v[28:31], v[34:37], 0
	ds_read_b128 v[28:31], v24
	v_mad_i32_i24 v24, v26, s50, v25
	ds_read_b128 v[24:27], v24
	s_waitcnt lgkmcnt(1)
	v_mfma_f32_16x16x32_bf16 v[46:49], v[28:31], v[34:37], 0
	v_add_f32_e64 v30, v4, v38
	v_add_f32_e64 v31, v5, v39
	v_pk_add_f32 v[28:29], v[6:7], v[40:41]
	s_nop 4
	v_pk_add_f32 v[10:11], v[10:11], v[48:49]
	s_waitcnt lgkmcnt(0)
	v_mfma_f32_16x16x32_bf16 v[34:37], v[24:27], v[34:37], 0
	v_add_f32_e64 v26, v12, v42
	v_add_f32_e64 v27, v13, v43
	v_pk_add_f32 v[24:25], v[14:15], v[44:45]
	v_pk_add_f32 v[12:13], v[8:9], v[46:47]
	s_nop 0
	v_mov_b32_e32 v4, v13
	s_nop 1
	v_pk_add_f32 v[6:7], v[2:3], v[36:37]
	v_mov_b32_e32 v2, v31
	v_mov_b32_e32 v3, v27
	v_pk_add_f32 v[8:9], v[0:1], v[34:35]
	v_mov_b32_e32 v0, v30
	v_mov_b32_e32 v1, v26
	v_pk_mul_f32 v[2:3], v[2:3], v[2:3]
	v_mov_b32_e32 v5, v9
	v_pk_fma_f32 v[0:1], v[0:1], v[0:1], v[2:3]
	v_mov_b32_e32 v2, v28
	v_mov_b32_e32 v3, v24
	v_pk_fma_f32 v[0:1], v[2:3], v[2:3], v[0:1]
	v_mov_b32_e32 v2, v29
	v_mov_b32_e32 v3, v25
	v_pk_fma_f32 v[0:1], v[2:3], v[2:3], v[0:1]
	v_mov_b32_e32 v2, v12
	v_mov_b32_e32 v3, v8
	v_pk_mul_f32 v[4:5], v[4:5], v[4:5]
	v_add_f32_e32 v0, v0, v1
	v_pk_fma_f32 v[2:3], v[2:3], v[2:3], v[4:5]
	v_mov_b32_e32 v4, v10
	v_mov_b32_e32 v5, v6
	v_pk_fma_f32 v[2:3], v[4:5], v[4:5], v[2:3]
	v_mov_b32_e32 v4, v11
	v_mov_b32_e32 v5, v7
	v_pk_fma_f32 v[2:3], v[4:5], v[4:5], v[2:3]
	v_xor_b32_e32 v1, 16, v198
	v_add_f32_e32 v0, v0, v2
	v_and_b32_e32 v2, 64, v198
	v_add_u32_e32 v2, 64, v2
	v_cmp_lt_i32_e64 s[0:1], v1, v2
	v_add_f32_e32 v0, v0, v3
	v_lshlrev_b32_e32 v35, 2, v33
	v_cndmask_b32_e64 v1, v198, v1, s[0:1]
	v_lshlrev_b32_e32 v1, 2, v1
	ds_bpermute_b32 v1, v1, v0
	v_lshlrev_b32_e32 v33, 16, v23
	v_and_b32_e32 v23, 0xffff0000, v23
	s_waitcnt lgkmcnt(0)
	v_add_f32_e32 v0, v0, v1
	v_xor_b32_e32 v1, 32, v198
	v_cmp_lt_i32_e64 s[0:1], v1, v2
	s_nop 1
	v_cndmask_b32_e64 v1, v198, v1, s[0:1]
	v_lshlrev_b32_e32 v1, 2, v1
	ds_bpermute_b32 v1, v1, v0
	s_waitcnt lgkmcnt(0)
	v_add_f32_e32 v0, v0, v1
	v_fmamk_f32 v0, v0, 0x3c800000, v193
	v_cmp_gt_f32_e64 s[0:1], s92, v0
	v_mul_f32_e32 v1, 0x4b800000, v0
	s_nop 0
	v_cndmask_b32_e64 v0, v0, v1, s[0:1]
	v_rsq_f32_e32 v0, v0
	s_nop 0
	v_mul_f32_e32 v1, 0x45800000, v0
	v_cndmask_b32_e64 v34, v0, v1, s[0:1]
	v_mov_b32_e32 v0, s8
	v_mov_b32_e32 v1, s9
	s_mov_b32 s0, 0x15603000
	v_cndmask_b32_e32 v0, v0, v1, vcc
	v_add_u32_e32 v0, v0, v32
	s_add_u32 s0, s76, s0
	v_ashrrev_i32_e32 v1, 31, v0
	s_addc_u32 s1, s77, 0
	v_lshlrev_b64 v[0:1], 11, v[0:1]
	v_lshl_add_u64 v[0:1], s[0:1], 0, v[0:1]
	s_lshl_b32 s96, s96, 1
	v_lshl_add_u64 v[0:1], v[0:1], 0, s[96:97]
	v_lshl_add_u64 v[14:15], v[0:1], 0, v[138:139]
	global_load_dwordx4 v[0:3], v35, s[2:3]
	global_load_dwordx4 v[210:213], v35, s[2:3] offset:64
	global_load_dwordx4 v[214:217], v35, s[2:3] offset:128
	global_load_dwordx4 v[218:221], v35, s[2:3] offset:192
	v_lshlrev_b32_e32 v32, 16, v22
	v_mul_f32_e32 v36, 0xbfb8aa3b, v32
	v_exp_f32_e32 v36, v36
	v_and_b32_e32 v22, 0xffff0000, v22
	v_mul_f32_e32 v30, v30, v34
	v_mul_f32_e32 v26, v26, v34
	v_add_f32_e32 v36, 1.0, v36
	v_rcp_f32_e32 v36, v36
	v_mul_f32_e32 v12, v12, v34
	s_mov_b64 s[0:1], 0x200
	v_lshl_add_u64 v[4:5], v[14:15], 0, s[0:1]
	v_mul_f32_e32 v32, v36, v32
	v_mul_f32_e32 v36, 0xbfb8aa3b, v22
	v_exp_f32_e32 v36, v36
	s_waitcnt vmcnt(3)
;   __device__ __forceinline__ bf16* h() const { unsigned o_ = (unsigned)(OFF_h); asm volatile("" : "+s"(o_)); return (bf16*)(ws + o_); }
;   __device__ __forceinline__ bf16* y() const { unsigned o_ = (unsigned)(OFF_y); asm volatile("" : "+s"(o_)); return (bf16*)(ws + o_); }
; __device__ __forceinline__ unsigned pk2(float a, float b) { unsigned r; asm("v_cvt_pk_bf16_f32 %0, %1, %2" : "=v"(r) : "v"(a), "v"(b)); return r; }
; __device__ __forceinline__ float lo16(unsigned v) { return __uint_as_float(v << 16); }
; __device__ __forceinline__ float hi16(unsigned v) { return __uint_as_float(v & 0xffff0000u); }
; __device__ __forceinline__ float sigm(float x) { return __builtin_amdgcn_rcpf(1.f + __expf(-x)); }
; __device__ __forceinline__ float silu(float x) { return x * sigm(x); }
; template <int MX>
; __device__ void out_unit(const P& p, int layer, int unit, char* smem) {
;     ...
;     bf16* yp = p.y() + TROW(qq) * D + (MX + 1) * 256 + h * 64 + 4 * q4;
; #pragma unroll
;     for (int et = 0; et < 4; ++et) {
;       const float4 g4 = *(const float4*)(ng + 16 * et);
;       const float t0 = lo16(gpre[et].x), t1 = hi16(gpre[et].x), t2 = lo16(gpre[et].y), t3 = hi16(gpre[et].y);
;       const float a0 = (MX == 1) ? sigm(t0) : silu(t0), a1 = (MX == 1) ? sigm(t1) : silu(t1), a2 = (MX == 1) ? sigm(t2) : silu(t2), a3 = (MX == 1) ? sigm(t3) : silu(t3);
;       uint2 ov2;
;       ov2.x = pk2(ov[et][0] * rms * g4.x * a0, ov[et][1] * rms * g4.y * a1);
;       ov2.y = pk2(ov[et][2] * rms * g4.z * a2, ov[et][3] * rms * g4.w * a3);
;       *(uint2*)(yp + 16 * et) = ov2;
;     }
	v_mul_f32_e32 v0, v0, v30
	v_add_f32_e32 v36, 1.0, v36
	v_rcp_f32_e32 v36, v36
	v_mul_f32_e32 v30, v31, v34
	v_mul_f32_e32 v1, v1, v30
	v_mul_f32_e32 v0, v32, v0
	v_mul_f32_e32 v22, v36, v22
	v_mul_f32_e32 v36, 0xbfb8aa3b, v33
	v_exp_f32_e32 v36, v36
	v_mul_f32_e32 v1, v22, v1
	v_cvt_pk_bf16_f32 v0, v0, v1
	v_mul_f32_e32 v1, v28, v34
	v_add_f32_e32 v36, 1.0, v36
	v_rcp_f32_e32 v36, v36
	v_mul_f32_e32 v1, v2, v1
	v_mul_f32_e32 v2, v29, v34
	v_mul_f32_e32 v2, v3, v2
	v_mul_f32_e32 v33, v36, v33
	v_mul_f32_e32 v36, 0xbfb8aa3b, v23
	v_exp_f32_e32 v36, v36
	v_mul_f32_e32 v1, v33, v1
	v_lshlrev_b32_e32 v22, 16, v20
	v_mul_f32_e32 v28, 0xbfb8aa3b, v22
	v_add_f32_e32 v36, 1.0, v36
	v_rcp_f32_e32 v36, v36
	v_exp_f32_e32 v28, v28
	v_and_b32_e32 v20, 0xffff0000, v20
	v_mov_b32_e32 v30, v208
	v_mul_f32_e32 v23, v36, v23
	v_mul_f32_e32 v2, v23, v2
	v_cvt_pk_bf16_f32 v1, v1, v2
	global_store_dwordx2 v[14:15], v[0:1], off offset:512
	s_waitcnt vmcnt(3)
	s_nop 0
	v_mov_b32_e32 v0, v210
	v_mov_b32_e32 v1, v211
	v_mov_b32_e32 v2, v212
	v_mov_b32_e32 v3, v213
	v_add_f32_e32 v28, 1.0, v28
	v_rcp_f32_e32 v28, v28
	v_lshlrev_b32_e32 v23, 16, v21
	v_and_b32_e32 v21, 0xffff0000, v21
	v_mul_f32_e32 v22, v28, v22
	v_mul_f32_e32 v28, 0xbfb8aa3b, v20
	v_exp_f32_e32 v28, v28
	s_nop 0
	v_mul_f32_e32 v0, v0, v26
	v_add_f32_e32 v28, 1.0, v28
	v_rcp_f32_e32 v28, v28
	v_mul_f32_e32 v0, v22, v0
	v_mul_f32_e32 v22, v27, v34
	v_mul_f32_e32 v1, v1, v22
	v_mul_f32_e32 v20, v28, v20
	v_mul_f32_e32 v28, 0xbfb8aa3b, v23
	v_exp_f32_e32 v28, v28
	v_mul_f32_e32 v1, v20, v1
	v_cvt_pk_bf16_f32 v0, v0, v1
	v_mul_f32_e32 v1, v24, v34
	v_add_f32_e32 v28, 1.0, v28
	v_rcp_f32_e32 v28, v28
	v_mul_f32_e32 v1, v2, v1
	v_mul_f32_e32 v2, v25, v34
	v_mul_f32_e32 v2, v3, v2
	v_mul_f32_e32 v23, v28, v23
	v_mul_f32_e32 v28, 0xbfb8aa3b, v21
	v_exp_f32_e32 v28, v28
	v_mul_f32_e32 v1, v23, v1
	v_lshlrev_b32_e32 v20, 16, v18
	v_mul_f32_e32 v22, 0xbfb8aa3b, v20
	v_add_f32_e32 v28, 1.0, v28
	v_rcp_f32_e32 v28, v28
	v_exp_f32_e32 v22, v22
	v_and_b32_e32 v18, 0xffff0000, v18
	v_mul_f32_e32 v23, v6, v34
	v_mul_f32_e32 v21, v28, v21
	v_mul_f32_e32 v2, v21, v2
	v_cvt_pk_bf16_f32 v1, v1, v2
	global_store_dwordx2 v[14:15], v[0:1], off offset:544
	s_waitcnt vmcnt(3)
	s_nop 0
	v_mov_b32_e32 v0, v214
	v_mov_b32_e32 v1, v215
	v_mov_b32_e32 v2, v216
	v_mov_b32_e32 v3, v217
	v_add_f32_e32 v22, 1.0, v22
	v_rcp_f32_e32 v22, v22
	v_lshlrev_b32_e32 v21, 16, v19
	v_and_b32_e32 v19, 0xffff0000, v19
	v_mul_f32_e32 v25, v7, v34
	v_mul_f32_e32 v20, v22, v20
	v_mul_f32_e32 v22, 0xbfb8aa3b, v18
	v_exp_f32_e32 v22, v22
	s_nop 0
	v_mul_f32_e32 v0, v12, v0
	v_add_f32_e32 v22, 1.0, v22
	v_rcp_f32_e32 v22, v22
	v_mul_f32_e32 v12, v13, v34
	v_mul_f32_e32 v1, v12, v1
	v_mul_f32_e32 v0, v20, v0
	v_mul_f32_e32 v18, v22, v18
	v_mul_f32_e32 v22, 0xbfb8aa3b, v21
	v_exp_f32_e32 v22, v22
	v_mul_f32_e32 v1, v18, v1
	v_cvt_pk_bf16_f32 v0, v0, v1
	v_mul_f32_e32 v1, v10, v34
	v_add_f32_e32 v22, 1.0, v22
	v_rcp_f32_e32 v22, v22
	v_mul_f32_e32 v1, v1, v2
	v_mul_f32_e32 v2, v11, v34
	v_mul_f32_e32 v2, v2, v3
	v_mul_f32_e32 v21, v22, v21
	v_mul_f32_e32 v22, 0xbfb8aa3b, v19
	v_exp_f32_e32 v22, v22
	v_mul_f32_e32 v1, v21, v1
	v_lshlrev_b32_e32 v10, 16, v16
	v_mul_f32_e32 v11, 0xbfb8aa3b, v10
	v_add_f32_e32 v22, 1.0, v22
	v_rcp_f32_e32 v22, v22
	v_exp_f32_e32 v11, v11
	v_and_b32_e32 v12, 0xffff0000, v16
	v_and_b32_e32 v16, 0xffff0000, v17
	v_mul_f32_e32 v19, v22, v19
	v_mul_f32_e32 v2, v19, v2
	v_cvt_pk_bf16_f32 v1, v1, v2
	global_store_dwordx2 v[14:15], v[0:1], off offset:576
	s_waitcnt vmcnt(3)
	s_nop 0
	v_mov_b32_e32 v0, v218
	v_mov_b32_e32 v1, v219
	v_mov_b32_e32 v2, v220
	v_mov_b32_e32 v3, v221
	v_add_f32_e32 v11, 1.0, v11
	v_rcp_f32_e32 v18, v11
	v_mul_f32_e32 v11, 0xbfb8aa3b, v12
	v_exp_f32_e32 v11, v11
	v_lshlrev_b32_e32 v14, 16, v17
	v_mul_f32_e32 v19, v8, v34
	v_mul_f32_e32 v21, v9, v34
	v_add_f32_e32 v11, 1.0, v11
	v_rcp_f32_e32 v20, v11
	v_mul_f32_e32 v11, 0xbfb8aa3b, v14
	v_exp_f32_e32 v11, v11
	s_nop 0
	v_mov_b32_e32 v13, v1
	v_add_f32_e32 v11, 1.0, v11
	v_rcp_f32_e32 v22, v11
	v_mul_f32_e32 v11, 0xbfb8aa3b, v16
	v_exp_f32_e32 v11, v11
	v_mov_b32_e32 v15, v2
	v_mov_b32_e32 v17, v3
	v_add_f32_e32 v11, 1.0, v11
	v_rcp_f32_e32 v24, v11
	v_mov_b32_e32 v11, v0
	v_pk_mul_f32 v[10:11], v[18:19], v[10:11]
	v_pk_mul_f32 v[0:1], v[20:21], v[12:13]
	v_mul_f32_e32 v8, v10, v11
	v_mul_f32_e32 v0, v0, v1
	v_cvt_pk_bf16_f32 v0, v8, v0
	v_pk_mul_f32 v[8:9], v[22:23], v[14:15]
	v_pk_mul_f32 v[2:3], v[24:25], v[16:17]
	v_mul_f32_e32 v1, v8, v9
	v_mul_f32_e32 v2, v2, v3
	v_cvt_pk_bf16_f32 v1, v1, v2

;   __device__ __forceinline__ bf16* h() const { unsigned o_ = (unsigned)(OFF_h); asm volatile("" : "+s"(o_)); return (bf16*)(ws + o_); }
; #define MFMA(a, b, c) __builtin_amdgcn_mfma_f32_16x16x32_bf16((a), (b), (c), 0, 0, 0)
; template <int MX>
; __device__ void out_unit(const P& p, int layer, int unit, char* smem) {
;     ...
; #pragma unroll
;   for (int kb = 0; kb < DK / 32; ++kb) {
;     const bf16x8 a = *(const bf16x8*)(Qs + (16 * w + r) * 72 + kb * 32 + q4 * 8);
; #pragma unroll
;     for (int et = 0; et < NE; ++et) {
;       const bf16x8 bs = *(const bf16x8*)(St + (16 * et + r) * 72 + kb * 32 + q4 * 8);
;       o2[et] = MFMA(bs, a, o2[et]);
;     }
;   }
;   const float* ng = ((MX == 0) ? p.gla_norm : (MX == 1 ? p.ml_norm : p.ret_norm)) + layer * 256 + h * 64 + 4 * q4;
;   {
;     const int qq = 16 * w + r;
;     float rsc = 1.f;
;     if (MX == 1) rsc = __expf(mprev - va[qq]);
;     if (MX == 2) rsc = exp2f((float)(qq + 1) * l2g);
;     f32x4 ov[4];
; #pragma unroll
;     for (int et = 0; et < 4; ++et) ov[et] = o[et] + o2[et] * rsc;
;     if (MX == 1) {
;       float den = o[NE - 1][0] + rsc * o2[NE - 1][0];
;       den = __shfl(den, r);
;       const float fl = __expf(-(vc[qq] + va[qq]));
;       const float inv = 1.f / fmaxf(fabsf(den), fl);
; #pragma unroll
;       for (int et = 0; et < 4; ++et) ov[et] = ov[et] * inv;
;     }
;     float ss = 0.f;
; #pragma unroll
;     for (int et = 0; et < 4; ++et) ss += ov[et][0] * ov[et][0] + ov[et][1] * ov[et][1] + ov[et][2] * ov[et][2] + ov[et][3] * ov[et][3];
;     ss += __shfl_xor(ss, 16); ss += __shfl_xor(ss, 32);
;     const float rms = rsqrtf(ss * (1.f / 64.f) + EPS);
.LBB0_671:
	s_or_b64 exec, exec, s[0:1]
	v_readlane_b32 s0, v254, 57
	s_nop 1
	v_lshl_add_u32 v1, v138, 1, s0
	v_mad_u32_u24 v2, v31, s50, v1
	v_mad_i32_i24 v3, v38, s50, v1
	v_mad_i32_i24 v72, v39, s50, v1
	v_mad_i32_i24 v73, v37, s50, v1
	v_mad_i32_i24 v1, v36, s50, v1
	ds_read_b128 v[40:43], v2
	ds_read_b128 v[44:47], v35
	ds_read_b128 v[48:51], v3
	ds_read_b128 v[60:63], v1
	ds_read_b128 v[52:55], v72
	ds_read_b128 v[56:59], v73
	ds_read_b128 v[64:67], v2 offset:64
	ds_read_b128 v[68:71], v35 offset:64
	s_waitcnt lgkmcnt(6)
	v_mfma_f32_16x16x32_bf16 v[38:41], v[40:43], v[44:47], 0
	s_lshl_b32 s0, s7, 2
	s_add_u32 s0, s63, s0
	s_addc_u32 s1, s64, 0
	s_waitcnt lgkmcnt(5)
	v_mfma_f32_16x16x32_bf16 v[48:51], v[48:51], v[44:47], 0
	s_waitcnt lgkmcnt(3)
	v_mfma_f32_16x16x32_bf16 v[52:55], v[52:55], v[44:47], 0
	s_waitcnt lgkmcnt(2)
	v_mfma_f32_16x16x32_bf16 v[56:59], v[56:59], v[44:47], 0
	v_mfma_f32_16x16x32_bf16 v[42:45], v[60:63], v[44:47], 0
	ds_read_b128 v[60:63], v3 offset:64
	ds_read_b32 v3, v34
	ds_read_b128 v[34:37], v72 offset:64
	s_waitcnt lgkmcnt(3)
	v_mfma_f32_16x16x32_bf16 v[38:41], v[64:67], v[68:71], v[38:41]
	ds_read_b128 v[64:67], v73 offset:64
	ds_read_b128 v[72:75], v1 offset:64
	s_waitcnt vmcnt(0) lgkmcnt(3)
	v_sub_f32_e32 v1, v32, v3
	v_mul_f32_e32 v1, 0x3fb8aa3b, v1
	v_exp_f32_e32 v2, v1
	v_lshl_add_u32 v1, v29, 2, v196
	v_add_u32_e32 v1, 0x19e00, v1
	ds_read_b32 v1, v1
	v_pk_fma_f32 v[18:19], v[40:41], v[2:3], v[18:19] op_sel_hi:[1,0,1]
	s_waitcnt lgkmcnt(1)
	v_mfma_f32_16x16x32_bf16 v[40:43], v[72:75], v[68:71], v[42:45]
	v_fma_f32 v16, v38, v2, v16
	v_fma_f32 v17, v39, v2, v17
	v_and_b32_e32 v38, 64, v198
	v_or_b32_e32 v31, v38, v31
	v_mfma_f32_16x16x32_bf16 v[46:49], v[60:63], v[68:71], v[48:51]
	v_lshlrev_b32_e32 v31, 2, v31
	s_nop 1
	v_fmac_f32_e32 v0, v40, v2
	ds_bpermute_b32 v31, v31, v0
	s_waitcnt lgkmcnt(1)
	v_add_f32_e32 v0, v3, v1
	v_mul_f32_e32 v0, 0xbfb8aa3b, v0
	v_pk_fma_f32 v[14:15], v[48:49], v[2:3], v[14:15] op_sel_hi:[1,0,1]
	v_exp_f32_e32 v3, v0
	v_mfma_f32_16x16x32_bf16 v[34:37], v[34:37], v[68:71], v[52:55]
	v_fma_f32 v0, v46, v2, v12
	v_fma_f32 v1, v47, v2, v13
	s_waitcnt lgkmcnt(0)
	v_max_f32_e64 v12, |v31|, |v31|
	v_max_f32_e32 v12, v12, v3
	v_div_scale_f32 v13, s[4:5], v12, v12, 1.0
	v_mfma_f32_16x16x32_bf16 v[50:53], v[64:67], v[68:71], v[56:59]
	v_rcp_f32_e32 v31, v13
	v_pk_fma_f32 v[10:11], v[36:37], v[2:3], v[10:11] op_sel_hi:[1,0,1]
	v_pk_fma_f32 v[8:9], v[34:35], v[2:3], v[8:9] op_sel_hi:[1,0,1]
	s_mov_b32 s4, 0x15603000
	s_nop 3
	v_pk_fma_f32 v[6:7], v[52:53], v[2:3], v[6:7] op_sel_hi:[1,0,1]
	v_pk_fma_f32 v[2:3], v[50:51], v[2:3], v[4:5] op_sel_hi:[1,0,1]
	v_fma_f32 v4, -v13, v31, 1.0
	v_fmac_f32_e32 v31, v4, v31
	v_div_scale_f32 v4, vcc, 1.0, v12, 1.0
	v_mul_f32_e32 v5, v4, v31
	v_fma_f32 v32, -v13, v5, v4
	v_fmac_f32_e32 v5, v32, v31
	v_fma_f32 v4, -v13, v5, v4
	v_div_fmas_f32 v4, v4, v31, v5
	v_div_fixup_f32 v12, v4, v12, 1.0
	v_pk_mul_f32 v[16:17], v[16:17], v[12:13] op_sel_hi:[1,0]
	v_pk_mul_f32 v[34:35], v[0:1], v[12:13] op_sel_hi:[1,0]
	v_pk_mul_f32 v[4:5], v[10:11], v[12:13] op_sel_hi:[1,0]
	v_pk_mul_f32 v[10:11], v[8:9], v[12:13] op_sel_hi:[1,0]
	v_mov_b32_e32 v8, v17
	v_mov_b32_e32 v9, v35
	v_pk_mul_f32 v[18:19], v[18:19], v[12:13] op_sel_hi:[1,0]
	v_pk_mul_f32 v[14:15], v[14:15], v[12:13] op_sel_hi:[1,0]
	v_pk_mul_f32 v[0:1], v[6:7], v[12:13] op_sel_hi:[1,0]
	v_mov_b32_e32 v6, v16
	v_mov_b32_e32 v7, v34
	v_pk_mul_f32 v[8:9], v[8:9], v[8:9]
	v_lshlrev_b32_e32 v31, 2, v33
	v_pk_fma_f32 v[6:7], v[6:7], v[6:7], v[8:9]
	v_mov_b32_e32 v8, v18
	v_mov_b32_e32 v9, v14
	v_pk_fma_f32 v[6:7], v[8:9], v[8:9], v[6:7]
	v_mov_b32_e32 v8, v19
	v_mov_b32_e32 v9, v15
	v_pk_mul_f32 v[2:3], v[2:3], v[12:13] op_sel_hi:[1,0]
	v_pk_fma_f32 v[12:13], v[8:9], v[8:9], v[6:7]
	global_load_dwordx4 v[6:9], v31, s[0:1]
	global_load_dwordx4 v[210:213], v31, s[0:1] offset:64
	global_load_dwordx4 v[214:217], v31, s[0:1] offset:128
	global_load_dwordx4 v[218:221], v31, s[0:1] offset:192
	v_mov_b32_e32 v32, v3
	v_mov_b32_e32 v33, v11
	v_mov_b32_e32 v36, v2
	v_mov_b32_e32 v37, v10
	v_pk_mul_f32 v[32:33], v[32:33], v[32:33]
	v_add_f32_e32 v12, v12, v13
	v_pk_fma_f32 v[32:33], v[36:37], v[36:37], v[32:33]
	v_mov_b32_e32 v36, v0
	v_mov_b32_e32 v37, v4
	v_pk_fma_f32 v[32:33], v[36:37], v[36:37], v[32:33]
	v_mov_b32_e32 v36, v1
	v_mov_b32_e32 v37, v5
	v_pk_fma_f32 v[32:33], v[36:37], v[36:37], v[32:33]
	v_xor_b32_e32 v13, 16, v198
	v_add_f32_e32 v12, v33, v12
	v_add_f32_e32 v12, v32, v12
	v_add_u32_e32 v32, 64, v38
	v_cmp_lt_i32_e32 vcc, v13, v32
	s_add_u32 s4, s76, s4
	s_addc_u32 s5, s77, 0
	v_cndmask_b32_e32 v13, v198, v13, vcc
	v_lshlrev_b32_e32 v13, 2, v13
	ds_bpermute_b32 v13, v13, v12
	s_lshl_b32 s96, s7, 1
	s_waitcnt lgkmcnt(0)
	v_add_f32_e32 v12, v12, v13
	v_xor_b32_e32 v13, 32, v198
	v_cmp_lt_i32_e32 vcc, v13, v32
	s_nop 1
	v_cndmask_b32_e32 v13, v198, v13, vcc
	v_lshlrev_b32_e32 v13, 2, v13
	ds_bpermute_b32 v13, v13, v12
	s_waitcnt lgkmcnt(0)
;   __device__ __forceinline__ bf16* h() const { unsigned o_ = (unsigned)(OFF_h); asm volatile("" : "+s"(o_)); return (bf16*)(ws + o_); }
;   __device__ __forceinline__ bf16* y() const { unsigned o_ = (unsigned)(OFF_y); asm volatile("" : "+s"(o_)); return (bf16*)(ws + o_); }
; __device__ __forceinline__ unsigned pk2(float a, float b) { unsigned r; asm("v_cvt_pk_bf16_f32 %0, %1, %2" : "=v"(r) : "v"(a), "v"(b)); return r; }
; __device__ __forceinline__ float lo16(unsigned v) { return __uint_as_float(v << 16); }
; __device__ __forceinline__ float hi16(unsigned v) { return __uint_as_float(v & 0xffff0000u); }
; __device__ __forceinline__ float sigm(float x) { return __builtin_amdgcn_rcpf(1.f + __expf(-x)); }
; __device__ __forceinline__ float silu(float x) { return x * sigm(x); }
; template <int MX>
; __device__ void out_unit(const P& p, int layer, int unit, char* smem) {
;     ...
;     const float rms = rsqrtf(ss * (1.f / 64.f) + EPS);
;     bf16* yp = p.y() + TROW(qq) * D + (MX + 1) * 256 + h * 64 + 4 * q4;
; #pragma unroll
;     for (int et = 0; et < 4; ++et) {
;       const float4 g4 = *(const float4*)(ng + 16 * et);
;       const float t0 = lo16(gpre[et].x), t1 = hi16(gpre[et].x), t2 = lo16(gpre[et].y), t3 = hi16(gpre[et].y);
;       const float a0 = (MX == 1) ? sigm(t0) : silu(t0), a1 = (MX == 1) ? sigm(t1) : silu(t1), a2 = (MX == 1) ? sigm(t2) : silu(t2), a3 = (MX == 1) ? sigm(t3) : silu(t3);
;       uint2 ov2;
;       ov2.x = pk2(ov[et][0] * rms * g4.x * a0, ov[et][1] * rms * g4.y * a1);
;       ov2.y = pk2(ov[et][2] * rms * g4.z * a2, ov[et][3] * rms * g4.w * a3);
;       *(uint2*)(yp + 16 * et) = ov2;
;     }
	v_add_f32_e32 v12, v12, v13
	v_fmamk_f32 v12, v12, 0x3c800000, v193
	v_mul_f32_e32 v13, 0x4b800000, v12
	v_cmp_gt_f32_e32 vcc, s92, v12
	s_nop 1
	v_cndmask_b32_e32 v12, v12, v13, vcc
	v_rsq_f32_e32 v12, v12
	s_nop 0
	v_mul_f32_e32 v13, 0x45800000, v12
	v_cndmask_b32_e32 v32, v12, v13, vcc
	v_cmp_gt_i32_e32 vcc, s44, v29
	v_mov_b32_e32 v12, s12
	v_mov_b32_e32 v13, s13
	s_and_b64 vcc, s[2:3], vcc
	v_cndmask_b32_e32 v12, v12, v13, vcc
	v_add_u32_e32 v12, v12, v29
	v_ashrrev_i32_e32 v13, 31, v12
	v_lshlrev_b64 v[12:13], 11, v[12:13]
	v_lshl_add_u64 v[12:13], s[4:5], 0, v[12:13]
	v_lshl_add_u64 v[12:13], v[12:13], 0, s[96:97]
	v_mov_b32_e32 v29, v139
	v_lshl_add_u64 v[12:13], v[12:13], 0, v[28:29]
	v_lshlrev_b32_e32 v28, 16, v26
	v_and_b32_e32 v26, 0xffff0000, v26
	v_mul_f32_e32 v28, 0xbfb8aa3b, v28
	v_mul_f32_e32 v26, 0xbfb8aa3b, v26
	v_exp_f32_e32 v28, v28
	v_exp_f32_e32 v26, v26
	v_lshlrev_b32_e32 v29, 16, v27
	v_and_b32_e32 v27, 0xffff0000, v27
	v_mul_f32_e32 v29, 0xbfb8aa3b, v29
	v_exp_f32_e32 v29, v29
	v_mul_f32_e32 v27, 0xbfb8aa3b, v27
	v_add_f32_e32 v28, 1.0, v28
	v_add_f32_e32 v26, 1.0, v26
	v_exp_f32_e32 v27, v27
	v_rcp_f32_e32 v28, v28
	v_rcp_f32_e32 v26, v26
	v_mul_f32_e32 v16, v16, v32
	v_add_f32_e32 v29, 1.0, v29
	s_waitcnt vmcnt(3)
	v_mul_f32_e32 v6, v6, v16
	v_mul_f32_e32 v16, v17, v32
	v_rcp_f32_e32 v29, v29
	v_add_f32_e32 v27, 1.0, v27
	v_mul_f32_e32 v7, v7, v16
	v_rcp_f32_e32 v27, v27
	v_mul_f32_e32 v6, v28, v6
	v_mul_f32_e32 v7, v26, v7
	v_cvt_pk_bf16_f32 v6, v6, v7
	v_mul_f32_e32 v7, v18, v32
	v_mul_f32_e32 v7, v8, v7
	v_mul_f32_e32 v8, v19, v32
	v_mul_f32_e32 v7, v29, v7
	v_mul_f32_e32 v8, v9, v8
	v_mul_f32_e32 v8, v27, v8
	v_cvt_pk_bf16_f32 v7, v7, v8
	global_store_dwordx2 v[12:13], v[6:7], off offset:1024
	s_waitcnt vmcnt(3)
	s_nop 0
	v_mov_b32_e32 v6, v210
	v_mov_b32_e32 v7, v211
	v_mov_b32_e32 v8, v212
	v_mov_b32_e32 v9, v213
	v_lshlrev_b32_e32 v16, 16, v24
	v_mul_f32_e32 v16, 0xbfb8aa3b, v16
	v_and_b32_e32 v17, 0xffff0000, v24
	v_exp_f32_e32 v16, v16
	v_mul_f32_e32 v17, 0xbfb8aa3b, v17
	v_exp_f32_e32 v17, v17
	v_lshlrev_b32_e32 v18, 16, v25
	v_and_b32_e32 v19, 0xffff0000, v25
	v_add_f32_e32 v16, 1.0, v16
	v_mul_f32_e32 v18, 0xbfb8aa3b, v18
	v_rcp_f32_e32 v16, v16
	v_exp_f32_e32 v18, v18
	v_mul_f32_e32 v19, 0xbfb8aa3b, v19
	v_add_f32_e32 v17, 1.0, v17
	v_exp_f32_e32 v19, v19
	v_rcp_f32_e32 v17, v17
	v_mul_f32_e32 v24, v34, v32
	v_add_f32_e32 v18, 1.0, v18
	v_rcp_f32_e32 v18, v18
	v_add_f32_e32 v19, 1.0, v19
	v_rcp_f32_e32 v19, v19
	v_mul_f32_e32 v5, v5, v32
	v_mul_f32_e32 v10, v10, v32
	v_mul_f32_e32 v11, v11, v32
	v_mul_f32_e32 v4, v4, v32
	v_mul_f32_e32 v1, v1, v32
	v_mul_f32_e32 v2, v2, v32
	v_mul_f32_e32 v3, v3, v32
	v_mul_f32_e32 v0, v0, v32
	s_nop 0
	v_mul_f32_e32 v6, v6, v24
	v_mul_f32_e32 v6, v16, v6
	v_mul_f32_e32 v16, v35, v32
	v_mul_f32_e32 v7, v7, v16
	v_mul_f32_e32 v7, v17, v7
	v_cvt_pk_bf16_f32 v6, v6, v7
	v_mul_f32_e32 v7, v14, v32
	v_mul_f32_e32 v7, v8, v7
	v_mul_f32_e32 v8, v15, v32
	v_mul_f32_e32 v7, v18, v7
	v_mul_f32_e32 v8, v9, v8
	v_mul_f32_e32 v8, v19, v8
	v_cvt_pk_bf16_f32 v7, v7, v8
	global_store_dwordx2 v[12:13], v[6:7], off offset:1056
	s_waitcnt vmcnt(3)
	s_nop 0
	v_mov_b32_e32 v6, v214
	v_mov_b32_e32 v7, v215
	v_mov_b32_e32 v8, v216
	v_mov_b32_e32 v9, v217
	v_and_b32_e32 v17, 0xffff0000, v23
	v_lshlrev_b32_e32 v14, 16, v22
	v_and_b32_e32 v15, 0xffff0000, v22
	v_lshlrev_b32_e32 v16, 16, v23
	v_mul_f32_e32 v17, 0xbfb8aa3b, v17
	v_mul_f32_e32 v14, 0xbfb8aa3b, v14
	v_mul_f32_e32 v15, 0xbfb8aa3b, v15
	v_mul_f32_e32 v16, 0xbfb8aa3b, v16
	v_exp_f32_e32 v17, v17
	v_exp_f32_e32 v14, v14
	v_exp_f32_e32 v15, v15
	v_exp_f32_e32 v16, v16
	v_add_f32_e32 v17, 1.0, v17
	v_add_f32_e32 v14, 1.0, v14
	v_add_f32_e32 v15, 1.0, v15
	v_add_f32_e32 v16, 1.0, v16
	v_rcp_f32_e32 v17, v17
	v_rcp_f32_e32 v14, v14
	v_rcp_f32_e32 v15, v15
	v_rcp_f32_e32 v16, v16
	s_nop 0
	v_mul_f32_e32 v5, v9, v5
	v_mul_f32_e32 v6, v6, v10
	v_mul_f32_e32 v7, v7, v11
	v_mul_f32_e32 v4, v8, v4
	v_mul_f32_e32 v5, v17, v5
	v_mul_f32_e32 v6, v14, v6
	v_mul_f32_e32 v7, v15, v7
	v_mul_f32_e32 v8, v16, v4
	v_cvt_pk_bf16_f32 v4, v6, v7
	v_cvt_pk_bf16_f32 v5, v8, v5
	global_store_dwordx2 v[12:13], v[4:5], off offset:1088
	s_waitcnt vmcnt(3)
	s_nop 0
	v_mov_b32_e32 v6, v218
	v_mov_b32_e32 v7, v219
	v_mov_b32_e32 v8, v220
	v_mov_b32_e32 v9, v221
	v_and_b32_e32 v11, 0xffff0000, v21
	v_lshlrev_b32_e32 v4, 16, v20
	v_and_b32_e32 v5, 0xffff0000, v20
	v_lshlrev_b32_e32 v10, 16, v21
	v_mul_f32_e32 v11, 0xbfb8aa3b, v11
	v_mul_f32_e32 v4, 0xbfb8aa3b, v4
	v_mul_f32_e32 v5, 0xbfb8aa3b, v5
	v_mul_f32_e32 v10, 0xbfb8aa3b, v10
	v_exp_f32_e32 v11, v11
	v_exp_f32_e32 v4, v4
	v_exp_f32_e32 v5, v5
	v_exp_f32_e32 v10, v10
	v_add_f32_e32 v11, 1.0, v11
	v_add_f32_e32 v4, 1.0, v4
	v_add_f32_e32 v5, 1.0, v5
	v_add_f32_e32 v10, 1.0, v10
	v_rcp_f32_e32 v11, v11
	v_rcp_f32_e32 v14, v4
	v_rcp_f32_e32 v15, v5
	v_rcp_f32_e32 v10, v10
	s_mov_b64 s[0:1], 0x400
	v_lshl_add_u64 v[4:5], v[12:13], 0, s[0:1]
	s_nop 0
	v_mul_f32_e32 v1, v1, v9
	v_mul_f32_e32 v2, v2, v6
	v_mul_f32_e32 v3, v3, v7
	v_mul_f32_e32 v0, v0, v8
	v_mul_f32_e32 v1, v11, v1
	v_mul_f32_e32 v2, v14, v2
	v_mul_f32_e32 v3, v15, v3
	v_mul_f32_e32 v6, v10, v0
	v_cvt_pk_bf16_f32 v0, v2, v3
	v_cvt_pk_bf16_f32 v1, v6, v1
	s_cbranch_execz .LBB0_509
	s_branch .LBB0_525

;   __device__ __forceinline__ bf16* y() const { unsigned o_ = (unsigned)(OFF_y); asm volatile("" : "+s"(o_)); return (bf16*)(ws + o_); }
; __device__ __forceinline__ float lo16(unsigned v) { return __uint_as_float(v << 16); }
; __device__ __forceinline__ float hi16(unsigned v) { return __uint_as_float(v & 0xffff0000u); }
; __device__ __forceinline__ float sigm(float x) { return __builtin_amdgcn_rcpf(1.f + __expf(-x)); }
; __device__ void phase_gemm_merge(const P& p, int layer, bf16* lds) {
;     ...
;   for (int it = 0; it < nit; ++it) {
;     const int br = it & 3;
;     int tm, tn; tile_coords(blockIdx.x + (it >> 2) * gridDim.x, NTN, tm, tn, NTM);
;     const int row0 = tm * 128, col0 = tn * 128;
; #pragma unroll
;     for (int a_ = 0; a_ < 4; ++a_)
; #pragma unroll
;       for (int b_ = 0; b_ < 2; ++b_) { acc[a_][b_] = f32x4{0.f, 0.f, 0.f, 0.f}; if (br == 0) macc[a_][b_] = f32x4{0.f, 0.f, 0.f, 0.f}; }
;     ...
; #pragma unroll
;     for (int nt = 0; nt < 4; ++nt) {
;       const int n = col0 + wn * 64 + (nt >> 1) * 32 + 8 * q + 4 * (nt & 1);
;       const float4 bm = *(const float4*)(p.b_merge + ((size_t)layer * 4 + br) * 1024 + n);
; #pragma unroll
;       for (int mt = 0; mt < 2; ++mt) {
;         const uint4 lg4 = greg[nt >> 1][mt];
;         const unsigned gx = (nt & 1) ? lg4.z : lg4.x, gy = (nt & 1) ? lg4.w : lg4.y;
;         macc[nt][mt][0] += sigm(lo16(gx) + bm.x) * acc[nt][mt][0];
;         macc[nt][mt][1] += sigm(hi16(gx) + bm.y) * acc[nt][mt][1];
;         macc[nt][mt][2] += sigm(lo16(gy) + bm.z) * acc[nt][mt][2];
;         macc[nt][mt][3] += sigm(hi16(gy) + bm.w) * acc[nt][mt][3];
;       }
;     }
.LBB0_732:
	s_lshl_b32 s1, s7, 10
	s_cmp_eq_u32 s7, 0
	s_cselect_b64 s[2:3], -1, 0
	v_or_b32_e32 v150, s0, v176
	s_lshl_b32 s0, s1, 2
	s_add_u32 s0, s5, s0
	s_addc_u32 s1, s6, 0
	v_ashrrev_i32_e32 v151, 31, v150
	v_lshl_add_u64 v[164:165], v[150:151], 2, s[0:1]
	v_cndmask_b32_e64 v167, v115, 0, s[2:3]
	v_cndmask_b32_e64 v166, v114, 0, s[2:3]
	v_cndmask_b32_e64 v169, v113, 0, s[2:3]
	v_cndmask_b32_e64 v168, v112, 0, s[2:3]
	s_waitcnt lgkmcnt(0)
	s_barrier
	global_load_dwordx4 v[112:115], v[164:165], off offset:16
	global_load_dwordx4 v[178:181], v[164:165], off
	global_load_dwordx4 v[246:249], v[164:165], off offset:144
	global_load_dwordx4 v[250:253], v[164:165], off offset:128
	s_waitcnt vmcnt(7)
	v_lshlrev_b32_e32 v117, 16, v92
	v_and_b32_e32 v92, 0xffff0000, v92
	v_cndmask_b32_e64 v123, v123, 0, s[2:3]
	v_cndmask_b32_e64 v122, v122, 0, s[2:3]
	v_cndmask_b32_e64 v129, v129, 0, s[2:3]
	v_cndmask_b32_e64 v128, v128, 0, s[2:3]
	v_cndmask_b32_e64 v131, v131, 0, s[2:3]
	v_cndmask_b32_e64 v130, v130, 0, s[2:3]
	v_cndmask_b32_e64 v133, v133, 0, s[2:3]
	v_cndmask_b32_e64 v132, v132, 0, s[2:3]
	v_cndmask_b32_e64 v127, v127, 0, s[2:3]
	v_cndmask_b32_e64 v126, v126, 0, s[2:3]
	v_cndmask_b32_e64 v161, v161, 0, s[2:3]
	v_cndmask_b32_e64 v160, v160, 0, s[2:3]
	v_cndmask_b32_e64 v157, v157, 0, s[2:3]
	v_cndmask_b32_e64 v156, v156, 0, s[2:3]
	v_cndmask_b32_e64 v155, v155, 0, s[2:3]
	v_cndmask_b32_e64 v154, v154, 0, s[2:3]
	v_cndmask_b32_e64 v153, v153, 0, s[2:3]
	v_cndmask_b32_e64 v152, v152, 0, s[2:3]
	v_cndmask_b32_e64 v149, v149, 0, s[2:3]
	v_cndmask_b32_e64 v148, v148, 0, s[2:3]
	v_cndmask_b32_e64 v121, v121, 0, s[2:3]
	v_cndmask_b32_e64 v120, v120, 0, s[2:3]
	v_cndmask_b32_e64 v163, v163, 0, s[2:3]
	v_cndmask_b32_e64 v162, v162, 0, s[2:3]
	v_cndmask_b32_e64 v159, v159, 0, s[2:3]
	v_cndmask_b32_e64 v158, v158, 0, s[2:3]
	v_cndmask_b32_e64 v135, v135, 0, s[2:3]
	v_cndmask_b32_e64 v134, v134, 0, s[2:3]
	s_cmp_lg_u32 s7, 3
	s_waitcnt vmcnt(2)
	v_add_f32_e32 v92, v179, v92
	v_mul_f32_e32 v92, 0xbfb8aa3b, v92
	v_exp_f32_e32 v92, v92
	v_add_f32_e32 v117, v178, v117
	v_mul_f32_e32 v117, 0xbfb8aa3b, v117
	v_exp_f32_e32 v117, v117
	v_add_f32_e32 v92, 1.0, v92
	v_rcp_f32_e32 v183, v92
	v_lshlrev_b32_e32 v92, 16, v93
	v_and_b32_e32 v93, 0xffff0000, v93
	v_add_f32_e32 v92, v180, v92
	v_add_f32_e32 v93, v181, v93
	v_mul_f32_e32 v92, 0xbfb8aa3b, v92
	v_mul_f32_e32 v93, 0xbfb8aa3b, v93
	v_exp_f32_e32 v92, v92
	v_exp_f32_e32 v93, v93
	v_add_f32_e32 v117, 1.0, v117
	v_rcp_f32_e32 v182, v117
	v_add_f32_e32 v92, 1.0, v92
	v_add_f32_e32 v93, 1.0, v93
	v_rcp_f32_e32 v92, v92
	v_rcp_f32_e32 v93, v93
	v_pk_fma_f32 v[120:121], v[108:109], v[182:183], v[120:121]
	v_pk_fma_f32 v[122:123], v[110:111], v[92:93], v[122:123]
	v_lshlrev_b32_e32 v92, 16, v88
	v_and_b32_e32 v88, 0xffff0000, v88
	v_add_f32_e32 v88, v179, v88
	v_mul_f32_e32 v88, 0xbfb8aa3b, v88
	v_exp_f32_e32 v88, v88
	v_add_f32_e32 v92, v178, v92
	v_mul_f32_e32 v92, 0xbfb8aa3b, v92
	v_exp_f32_e32 v92, v92
	v_add_f32_e32 v88, 1.0, v88
	v_rcp_f32_e32 v93, v88
	v_lshlrev_b32_e32 v88, 16, v89
	v_and_b32_e32 v89, 0xffff0000, v89
	v_add_f32_e32 v88, v180, v88
	v_add_f32_e32 v89, v181, v89
	v_mul_f32_e32 v88, 0xbfb8aa3b, v88
	v_mul_f32_e32 v89, 0xbfb8aa3b, v89
	v_exp_f32_e32 v88, v88
	v_exp_f32_e32 v89, v89
	v_add_f32_e32 v92, 1.0, v92
	v_rcp_f32_e32 v92, v92
	v_add_f32_e32 v88, 1.0, v88
	v_add_f32_e32 v89, 1.0, v89
	v_rcp_f32_e32 v88, v88
	v_rcp_f32_e32 v89, v89
	v_pk_fma_f32 v[126:127], v[104:105], v[92:93], v[126:127]
	v_pk_fma_f32 v[128:129], v[106:107], v[88:89], v[128:129]
	v_lshlrev_b32_e32 v88, 16, v94
	v_and_b32_e32 v89, 0xffff0000, v94
	v_add_f32_e32 v88, v112, v88
	v_add_f32_e32 v89, v113, v89
	v_mul_f32_e32 v88, 0xbfb8aa3b, v88
	v_mul_f32_e32 v89, 0xbfb8aa3b, v89
	v_exp_f32_e32 v88, v88
	v_exp_f32_e32 v89, v89
	v_add_f32_e32 v88, 1.0, v88
	v_add_f32_e32 v89, 1.0, v89
	v_rcp_f32_e32 v88, v88
	v_rcp_f32_e32 v89, v89
	s_nop 0
	v_pk_fma_f32 v[130:131], v[100:101], v[88:89], v[130:131]
	v_lshlrev_b32_e32 v88, 16, v95
	v_and_b32_e32 v89, 0xffff0000, v95
	v_add_f32_e32 v88, v114, v88
	v_add_f32_e32 v89, v115, v89
	v_mul_f32_e32 v88, 0xbfb8aa3b, v88
	v_mul_f32_e32 v89, 0xbfb8aa3b, v89
	v_exp_f32_e32 v88, v88
	v_exp_f32_e32 v89, v89
	v_add_f32_e32 v88, 1.0, v88
	v_add_f32_e32 v89, 1.0, v89
	v_rcp_f32_e32 v88, v88
	v_rcp_f32_e32 v89, v89
	s_nop 0
	v_pk_fma_f32 v[132:133], v[102:103], v[88:89], v[132:133]
	v_lshlrev_b32_e32 v88, 16, v90
	v_and_b32_e32 v89, 0xffff0000, v90
	v_add_f32_e32 v88, v112, v88
	v_add_f32_e32 v89, v113, v89
	v_mul_f32_e32 v88, 0xbfb8aa3b, v88
	v_mul_f32_e32 v89, 0xbfb8aa3b, v89
	v_exp_f32_e32 v88, v88
	v_exp_f32_e32 v89, v89
	v_add_f32_e32 v88, 1.0, v88
	v_add_f32_e32 v89, 1.0, v89
	v_rcp_f32_e32 v88, v88
	v_rcp_f32_e32 v89, v89
	s_nop 0
	v_pk_fma_f32 v[112:113], v[96:97], v[88:89], v[168:169]
	v_lshlrev_b32_e32 v88, 16, v91
	v_and_b32_e32 v89, 0xffff0000, v91
	v_add_f32_e32 v88, v114, v88
	v_add_f32_e32 v89, v115, v89
	v_mul_f32_e32 v88, 0xbfb8aa3b, v88
	v_mul_f32_e32 v89, 0xbfb8aa3b, v89
	v_exp_f32_e32 v88, v88
	v_exp_f32_e32 v89, v89
	v_lshlrev_b32_e32 v96, 16, v68
	v_and_b32_e32 v68, 0xffff0000, v68
	v_add_f32_e32 v88, 1.0, v88
	v_add_f32_e32 v89, 1.0, v89
	v_rcp_f32_e32 v88, v88
	v_rcp_f32_e32 v89, v89
	s_nop 0
	v_pk_fma_f32 v[114:115], v[98:99], v[88:89], v[166:167]
	s_nop 0
	s_nop 0
	s_waitcnt vmcnt(0)
;   __device__ __forceinline__ bf16* xn() const { unsigned o_ = (unsigned)(OFF_xn); asm volatile("" : "+s"(o_)); return (bf16*)(ws + o_); }
;   __device__ __forceinline__ bf16* y() const { unsigned o_ = (unsigned)(OFF_y); asm volatile("" : "+s"(o_)); return (bf16*)(ws + o_); }
; __device__ __forceinline__ unsigned pk2(float a, float b) { unsigned r; asm("v_cvt_pk_bf16_f32 %0, %1, %2" : "=v"(r) : "v"(a), "v"(b)); return r; }
; __device__ __forceinline__ float lo16(unsigned v) { return __uint_as_float(v << 16); }
; __device__ __forceinline__ float hi16(unsigned v) { return __uint_as_float(v & 0xffff0000u); }
; __device__ __forceinline__ float sigm(float x) { return __builtin_amdgcn_rcpf(1.f + __expf(-x)); }
; __device__ void phase_gemm_merge(const P& p, int layer, bf16* lds) {
;     ...
; #pragma unroll
;     for (int nt = 0; nt < 4; ++nt) {
;       const int n = col0 + wn * 64 + (nt >> 1) * 32 + 8 * q + 4 * (nt & 1);
;       const float4 bm = *(const float4*)(p.b_merge + ((size_t)layer * 4 + br) * 1024 + n);
; #pragma unroll
;       for (int mt = 0; mt < 2; ++mt) {
;         const uint4 lg4 = greg[nt >> 1][mt];
;         const unsigned gx = (nt & 1) ? lg4.z : lg4.x, gy = (nt & 1) ? lg4.w : lg4.y;
;         macc[nt][mt][0] += sigm(lo16(gx) + bm.x) * acc[nt][mt][0];
;         macc[nt][mt][1] += sigm(hi16(gx) + bm.y) * acc[nt][mt][1];
;         macc[nt][mt][2] += sigm(lo16(gy) + bm.z) * acc[nt][mt][2];
;         macc[nt][mt][3] += sigm(hi16(gy) + bm.w) * acc[nt][mt][3];
;       }
;     }
;     if (br == 3) {
; #pragma unroll
;       for (int pr = 0; pr < 2; ++pr) {
;         const int n = col0 + wn * 64 + pr * 32 + 8 * q;
; #pragma unroll
;         for (int mt = 0; mt < 2; ++mt) {
;           const int m = row0 + wm * 32 + mt * 16 + r;
;           uint4 o;
;           o.x = pk2(macc[2 * pr][mt][0], macc[2 * pr][mt][1]); o.y = pk2(macc[2 * pr][mt][2], macc[2 * pr][mt][3]);
;           o.z = pk2(macc[2 * pr + 1][mt][0], macc[2 * pr + 1][mt][1]); o.w = pk2(macc[2 * pr + 1][mt][2], macc[2 * pr + 1][mt][3]);
;           *(uint4*)(p.xn() + (size_t)m * D + n) = o;
;         }
;       }
;     }
	v_add_f32_e32 v68, v251, v68
	v_mul_f32_e32 v68, 0xbfb8aa3b, v68
	v_exp_f32_e32 v68, v68
	v_add_f32_e32 v96, v250, v96
	v_mul_f32_e32 v96, 0xbfb8aa3b, v96
	v_exp_f32_e32 v96, v96
	v_add_f32_e32 v68, 1.0, v68
	v_rcp_f32_e32 v97, v68
	v_lshlrev_b32_e32 v68, 16, v69
	v_and_b32_e32 v69, 0xffff0000, v69
	v_add_f32_e32 v68, v252, v68
	v_add_f32_e32 v69, v253, v69
	v_mul_f32_e32 v68, 0xbfb8aa3b, v68
	v_mul_f32_e32 v69, 0xbfb8aa3b, v69
	v_exp_f32_e32 v68, v68
	v_exp_f32_e32 v69, v69
	v_add_f32_e32 v96, 1.0, v96
	v_rcp_f32_e32 v96, v96
	v_add_f32_e32 v68, 1.0, v68
	v_add_f32_e32 v69, 1.0, v69
	v_rcp_f32_e32 v68, v68
	v_rcp_f32_e32 v69, v69
	v_pk_fma_f32 v[162:163], v[84:85], v[96:97], v[162:163]
	v_pk_fma_f32 v[160:161], v[86:87], v[68:69], v[160:161]
	v_lshlrev_b32_e32 v68, 16, v64
	v_and_b32_e32 v64, 0xffff0000, v64
	v_add_f32_e32 v64, v251, v64
	v_mul_f32_e32 v64, 0xbfb8aa3b, v64
	v_exp_f32_e32 v64, v64
	v_add_f32_e32 v68, v250, v68
	v_mul_f32_e32 v68, 0xbfb8aa3b, v68
	v_exp_f32_e32 v68, v68
	v_add_f32_e32 v64, 1.0, v64
	v_rcp_f32_e32 v69, v64
	v_lshlrev_b32_e32 v64, 16, v65
	v_and_b32_e32 v65, 0xffff0000, v65
	v_add_f32_e32 v64, v252, v64
	v_add_f32_e32 v65, v253, v65
	v_mul_f32_e32 v64, 0xbfb8aa3b, v64
	v_mul_f32_e32 v65, 0xbfb8aa3b, v65
	v_exp_f32_e32 v64, v64
	v_exp_f32_e32 v65, v65
	v_add_f32_e32 v68, 1.0, v68
	v_rcp_f32_e32 v68, v68
	v_add_f32_e32 v64, 1.0, v64
	v_add_f32_e32 v65, 1.0, v65
	v_rcp_f32_e32 v64, v64
	v_rcp_f32_e32 v65, v65
	v_pk_fma_f32 v[158:159], v[80:81], v[68:69], v[158:159]
	v_pk_fma_f32 v[156:157], v[82:83], v[64:65], v[156:157]
	v_lshlrev_b32_e32 v64, 16, v70
	v_and_b32_e32 v65, 0xffff0000, v70
	v_add_f32_e32 v64, v246, v64
	v_add_f32_e32 v65, v247, v65
	v_mul_f32_e32 v64, 0xbfb8aa3b, v64
	v_mul_f32_e32 v65, 0xbfb8aa3b, v65
	v_exp_f32_e32 v64, v64
	v_exp_f32_e32 v65, v65
	v_add_f32_e32 v64, 1.0, v64
	v_add_f32_e32 v65, 1.0, v65
	v_rcp_f32_e32 v64, v64
	v_rcp_f32_e32 v65, v65
	s_nop 0
	v_pk_fma_f32 v[154:155], v[76:77], v[64:65], v[154:155]
	v_lshlrev_b32_e32 v64, 16, v71
	v_and_b32_e32 v65, 0xffff0000, v71
	v_add_f32_e32 v64, v248, v64
	v_add_f32_e32 v65, v249, v65
	v_mul_f32_e32 v64, 0xbfb8aa3b, v64
	v_mul_f32_e32 v65, 0xbfb8aa3b, v65
	v_exp_f32_e32 v64, v64
	v_exp_f32_e32 v65, v65
	v_add_f32_e32 v64, 1.0, v64
	v_add_f32_e32 v65, 1.0, v65
	v_rcp_f32_e32 v64, v64
	v_rcp_f32_e32 v65, v65
	s_nop 0
	v_pk_fma_f32 v[152:153], v[78:79], v[64:65], v[152:153]
	v_lshlrev_b32_e32 v64, 16, v66
	v_and_b32_e32 v65, 0xffff0000, v66
	v_add_f32_e32 v64, v246, v64
	v_add_f32_e32 v65, v247, v65
	v_mul_f32_e32 v64, 0xbfb8aa3b, v64
	v_mul_f32_e32 v65, 0xbfb8aa3b, v65
	v_exp_f32_e32 v64, v64
	v_exp_f32_e32 v65, v65
	v_add_f32_e32 v64, 1.0, v64
	v_add_f32_e32 v65, 1.0, v65
	v_rcp_f32_e32 v64, v64
	v_rcp_f32_e32 v65, v65
	s_nop 0
	v_pk_fma_f32 v[148:149], v[72:73], v[64:65], v[148:149]
	v_lshlrev_b32_e32 v64, 16, v67
	v_and_b32_e32 v65, 0xffff0000, v67
	v_add_f32_e32 v64, v248, v64
	v_add_f32_e32 v65, v249, v65
	v_mul_f32_e32 v64, 0xbfb8aa3b, v64
	v_mul_f32_e32 v65, 0xbfb8aa3b, v65
	v_exp_f32_e32 v64, v64
	v_exp_f32_e32 v65, v65
	v_add_f32_e32 v64, 1.0, v64
	v_add_f32_e32 v65, 1.0, v65
	v_rcp_f32_e32 v64, v64
	v_rcp_f32_e32 v65, v65
	s_nop 0
	v_pk_fma_f32 v[134:135], v[74:75], v[64:65], v[134:135]
	s_cbranch_scc1 .LBB0_727
	s_mov_b32 s0, 0x4100000
	v_ashrrev_i32_e32 v125, 31, v124
	s_add_u32 s0, s76, s0
	s_addc_u32 s1, s77, 0
	v_lshlrev_b64 v[68:69], 11, v[124:125]
	v_lshl_add_u64 v[70:71], s[0:1], 0, v[68:69]
	v_lshlrev_b64 v[72:73], 1, v[150:151]
	v_lshl_add_u64 v[70:71], v[70:71], 0, v[72:73]
	s_mov_b32 s0, 0x4100000
	v_cvt_pk_bf16_f32 v64, v120, v121
	v_cvt_pk_bf16_f32 v65, v122, v123
	v_cvt_pk_bf16_f32 v66, v130, v131
	v_cvt_pk_bf16_f32 v67, v132, v133
	global_store_dwordx4 v[70:71], v[64:67], off
	v_or_b32_e32 v70, 16, v124
	s_add_u32 s0, s76, s0
	v_ashrrev_i32_e32 v71, 31, v70
	s_addc_u32 s1, s77, 0
	v_lshlrev_b64 v[70:71], 11, v[70:71]
	v_lshl_add_u64 v[74:75], s[0:1], 0, v[70:71]
	v_lshl_add_u64 v[74:75], v[74:75], 0, v[72:73]
	s_mov_b32 s0, 0x4100000
	v_cvt_pk_bf16_f32 v64, v126, v127
	v_cvt_pk_bf16_f32 v65, v128, v129
	v_cvt_pk_bf16_f32 v66, v112, v113
	v_cvt_pk_bf16_f32 v67, v114, v115
	global_store_dwordx4 v[74:75], v[64:67], off
	s_add_u32 s0, s76, s0
	s_addc_u32 s1, s77, 0
	v_lshl_add_u64 v[68:69], s[0:1], 0, v[68:69]
	v_lshl_add_u64 v[68:69], v[68:69], 0, v[72:73]
	s_mov_b32 s0, 0x4100000
	v_cvt_pk_bf16_f32 v64, v162, v163
	v_cvt_pk_bf16_f32 v65, v160, v161
	v_cvt_pk_bf16_f32 v66, v154, v155
	v_cvt_pk_bf16_f32 v67, v152, v153
	global_store_dwordx4 v[68:69], v[64:67], off offset:64
	s_add_u32 s0, s76, s0
	s_addc_u32 s1, s77, 0
	v_lshl_add_u64 v[68:69], s[0:1], 0, v[70:71]
	v_lshl_add_u64 v[68:69], v[68:69], 0, v[72:73]
	v_cvt_pk_bf16_f32 v64, v158, v159
	v_cvt_pk_bf16_f32 v65, v156, v157
	v_cvt_pk_bf16_f32 v66, v148, v149
	v_cvt_pk_bf16_f32 v67, v134, v135
	global_store_dwordx4 v[68:69], v[64:67], off offset:64
	s_branch .LBB0_727
